# phase-dependent static priority: s_setprio 1 for memory-bound segments (P7 convert, P8 v-side gather), 0 for VALU-bound topk / u-side
# baseline (speedup 1.0000x reference)
; __global__ void __launch_bounds__(NTHR, 2) fwd_kernel(Params p) {
;     ...
;   if (PHASE_ON(7)) {
;     const int u_first = blockIdx.x * 2 + hb, u_step = gridDim.x * 2;
;     const int nk = u_first < 2048 ? (2048 - u_first + u_step - 1) / u_step : 0;
;     if (nk == 0) convert_uv(p, 0, 1);
.LBB0_1057:
	s_setprio 1
	s_cmp_lt_i32 s56, 8
	s_cselect_b64 s[20:21], -1, 0
	s_and_b64 s[0:1], s[20:21], s[0:1]
	s_andn2_b64 vcc, exec, s[0:1]
	s_cbranch_vccnz .LBB0_1131
	s_movk_i32 s0, 0x800
	s_lshl_b32 s33, s96, 1
	v_cmp_gt_i32_e64 s[0:1], s0, v167
	v_mov_b32_e32 v1, 0
	s_and_saveexec_b64 s[4:5], s[0:1]
	s_cbranch_execz .LBB0_1060
	s_abs_i32 s3, s33
	v_cvt_f32_u32_e32 v1, s3
	v_sub_u32_e32 v2, s33, v167
	s_waitcnt lgkmcnt(0)
	v_add_u32_e32 v3, 0x7ff, v2
	v_sub_u32_e32 v2, 0xfffff801, v2
	v_rcp_iflag_f32_e32 v1, v1
	s_sub_i32 s6, 0, s3
	v_xor_b32_e32 v4, s33, v3
	v_max_i32_e32 v2, v3, v2
	v_mul_f32_e32 v1, 0x4f7ffffe, v1
	v_cvt_u32_f32_e32 v1, v1
	v_ashrrev_i32_e32 v3, 31, v4
	v_mul_lo_u32 v4, s6, v1
	v_mul_hi_u32 v4, v1, v4
	v_add_u32_e32 v1, v1, v4
	v_mul_hi_u32 v1, v2, v1
	v_mul_lo_u32 v4, v1, s3
	v_sub_u32_e32 v2, v2, v4
	v_add_u32_e32 v5, 1, v1
	v_cmp_le_u32_e32 vcc, s3, v2
	v_subrev_u32_e32 v4, s3, v2
	s_nop 0
	v_cndmask_b32_e32 v1, v1, v5, vcc
	v_cndmask_b32_e32 v2, v2, v4, vcc
	v_add_u32_e32 v4, 1, v1
	v_cmp_le_u32_e32 vcc, s3, v2
	s_nop 1
	v_cndmask_b32_e32 v1, v1, v4, vcc
	v_xor_b32_e32 v1, v1, v3
	v_sub_u32_e32 v1, v1, v3

; __device__ void topk_unit(const Params& p, unsigned char* smem, int unit) {
;   const int tid = threadIdx.x & 255, lane = tid & 63, wid = tid >> 6, l15 = lane & 15, q4 = lane >> 4;
;   const int h = unit & 7, tile = unit >> 3;
;   const int tok0 = tile * 64 + wid * 16;
;   unsigned char* ws = p.ws;
;   const bf16_t* qg = (const bf16_t*)(ws + OFF_Q);
;   const bf16_t* kb = (const bf16_t*)(ws + OFF_KEYSB);
;   unsigned* S = (unsigned*)(smem + wid * 16640);
;   float* tops = (float*)(smem + 4 * 16640 + wid * 256);
;   int* topi = (int*)(tops + 32);
;   unsigned* Ms = (unsigned*)(smem + 67584 + wid * 768);
; #pragma unroll
;   for (int k = 0; k < 2; ++k) {
;     f32x4 sc[8];
; #pragma unroll
;     for (int i = 0; i < 8; ++i) sc[i] = (f32x4){0, 0, 0, 0};
; #pragma unroll
;     for (int ks = 0; ks < 4; ++ks) {
;       bf16x8 qf = as_frag(*(const u32x4*)(qg + (size_t)(tok0 + l15) * DM + h * 256 + k * 128 + ks * 32 + q4 * 8));
; #pragma unroll
;       for (int nt = 0; nt < 8; ++nt) {
;         bf16x8 kf = as_frag(*(const u32x4*)(kb + (size_t)((h * 2 + k) * 128 + nt * 16 + l15) * 128 + ks * 32 + q4 * 8));
;         sc[nt] = mfma16(kf, qf, sc[nt]);
;       }
;     }
; #pragma unroll
;     for (int nt = 0; nt < 8; ++nt) {
;       const int n = nt * 16 + q4 * 4;
;       u32x4 kk;
; #pragma unroll
;       for (int r = 0; r < 4; ++r) kk[r] = (ord_key(sc[nt][r]) & ~127u) | (unsigned)(127 - (n + r));
;       *(u32x4*)(S + l15 * 260 + k * 128 + n) = kk;
;     }
;   }
;   const unsigned ct = cand_tab[lane];
;   const int ca = ct >> 4, cbb = ct & 15;
;   int* idxo = (int*)(ws + OFF_IDX);
;   float* go = (float*)(ws + OFF_G);
.LBB0_1082:
	s_setprio 0
	s_or_b64 exec, exec, s[10:11]
	s_and_saveexec_b64 s[22:23], s[0:1]
	s_cbranch_execz .LBB0_1130
	s_add_u32 s36, s34, 0x8000000
	s_addc_u32 s37, s35, 0
	s_getpc_b64 s[0:1]
	s_add_u32 s0, s0, _ZL8cand_tab@rel32@lo+4
	s_addc_u32 s1, s1, _ZL8cand_tab@rel32@hi+12
	global_load_ubyte v65, v138, s[0:1]
	s_waitcnt lgkmcnt(0)
	v_lshlrev_b64 v[2:3], v139, -1
	v_mbcnt_lo_u32_b32 v10, -1, 0
	v_mul_lo_u32 v5, s96, v1
	v_bfe_u32 v1, v139, 6, 2
	v_and_b32_e32 v96, 15, v139
	v_bfe_u32 v7, v139, 4, 2
	s_movk_i32 s3, 0x4100
	v_not_b32_e32 v64, v2
	v_mbcnt_hi_u32_b32 v2, -1, v10
	v_and_b32_e32 v62, 48, v139
	v_lshlrev_b32_e32 v12, 2, v138
	v_mad_u32_u24 v13, v1, s3, v166
	v_lshlrev_b32_e32 v6, 3, v7
	v_lshlrev_b32_e32 v98, 2, v7
	v_mul_u32_u24_e32 v7, 0x410, v96
	v_and_b32_e32 v102, 64, v2
	v_mov_b32_e32 v63, 0
	v_lshlrev_b32_e32 v97, 4, v1
	v_lshlrev_b32_e32 v14, 8, v1
	v_mul_u32_u24_e32 v15, 0x300, v1
	v_not_b32_e32 v1, v3
	v_add3_u32 v100, v13, v7, v62
	v_xor_b32_e32 v3, 32, v2
	v_add_u32_e32 v103, v13, v12
	v_add_u32_e32 v13, 64, v102
	s_mov_b64 s[0:1], 0x1d740000
	s_mov_b64 s[6:7], 0x1d740040
	s_mov_b64 s[8:9], 0x1d740080
	s_mov_b64 s[10:11], 0x1d7400c0
	v_lshl_add_u64 v[8:9], s[34:35], 0, v[62:63]
	v_xor_b32_e32 v7, 16, v2
	v_cmp_lt_i32_e32 vcc, v3, v13
	v_lshl_add_u64 v[66:67], v[8:9], 0, s[0:1]
	v_lshl_add_u64 v[68:69], v[8:9], 0, s[6:7]
	v_lshl_add_u64 v[70:71], v[8:9], 0, s[8:9]
	v_lshl_add_u64 v[72:73], v[8:9], 0, s[10:11]
	v_xor_b32_e32 v8, 8, v2
	v_cndmask_b32_e32 v3, v2, v3, vcc
	v_cmp_lt_i32_e32 vcc, v7, v13
	v_xor_b32_e32 v9, 4, v2
	s_mov_b32 s12, 0x10400
	v_cndmask_b32_e32 v7, v2, v7, vcc
	v_cmp_lt_i32_e32 vcc, v8, v13
	v_xor_b32_e32 v10, 2, v2
	v_add3_u32 v99, v166, v14, s12
	v_cndmask_b32_e32 v8, v2, v8, vcc
	v_cmp_lt_i32_e32 vcc, v9, v13
	v_xor_b32_e32 v14, 1, v2
	s_add_u32 s38, s34, 0xc000000
	v_cndmask_b32_e32 v9, v2, v9, vcc
	v_cmp_lt_i32_e32 vcc, v10, v13
	v_lshlrev_b32_e32 v106, 2, v3
	s_addc_u32 s39, s35, 0
	v_cndmask_b32_e32 v10, v2, v10, vcc
	v_cmp_lt_i32_e32 vcc, v14, v13
	s_add_u32 s40, s34, 0xc800000
	s_mov_b32 s13, 0x10800
	v_cndmask_b32_e32 v2, v2, v14, vcc
	v_lshlrev_b32_e32 v111, 2, v2
	s_addc_u32 s41, s35, 0
	v_lshlrev_b32_e32 v74, 3, v5
	s_lshl_b32 s49, s96, 4
	s_lshl_b32 s0, s2, 1
	v_and_b32_e32 v11, 31, v139
	v_lshlrev_b32_e32 v4, 5, v138
	v_add3_u32 v101, v166, v15, s13
	v_lshlrev_b32_e32 v62, 4, v138
	v_ashrrev_i32_e32 v75, 31, v74
	s_mov_b32 s48, 0
	v_cmp_gt_u32_e64 s[14:15], 32, v138
	v_cmp_gt_u32_e64 s[4:5], 50, v138
	v_add_u32_e32 v104, v101, v12
	v_lshl_add_u32 v105, v11, 2, v101
	v_lshlrev_b32_e32 v107, 2, v7
	v_lshlrev_b32_e32 v108, 2, v8
	v_lshlrev_b32_e32 v109, 2, v9
	v_lshlrev_b32_e32 v110, 2, v10
	v_cmp_eq_u32_e64 s[6:7], 0, v138
	v_add_u16_e32 v115, s0, v165
	s_waitcnt vmcnt(0)
	v_lshrrev_b32_e32 v3, 2, v65
	v_and_b32_e32 v2, 15, v65
	v_and_b32_e32 v3, 60, v3
	v_lshl_add_u32 v112, v2, 2, v99
	v_add_u32_e32 v113, v99, v3
	v_lshlrev_b32_e32 v2, 7, v138
	v_mov_b32_e32 v3, v63
	v_lshl_add_u64 v[76:77], s[18:19], 0, v[2:3]
	v_lshlrev_b32_e32 v2, 3, v165
	v_lshl_add_u32 v114, s2, 4, v2
	s_add_u32 s18, s34, 0x1dc90000
	v_lshlrev_b32_e32 v2, 11, v164
	s_addc_u32 s19, s35, 0
	v_lshl_add_u32 v78, s2, 3, v164
	s_lshl_b32 s50, s96, 3
	v_lshlrev_b64 v[80:81], 2, v[74:75]
	v_lshl_add_u64 v[82:83], s[34:35], 0, v[62:63]
	v_lshlrev_b64 v[84:85], 10, v[74:75]
	v_lshl_add_u32 v75, s2, 14, v2
	s_lshl_b32 s51, s96, 14
	v_lshlrev_b32_e32 v116, 14, v5
	s_mov_b64 s[42:43], 0
	s_movk_i32 s52, 0xffc0
	v_lshlrev_b32_e32 v86, 1, v6
	v_mov_b32_e32 v87, v63
	v_lshlrev_b32_e32 v117, 8, v96
	s_movk_i32 s53, 0x4000
	v_bfrev_b32_e32 v118, 1
	s_movk_i32 s54, 0xff80
	s_movk_i32 s55, 0x7f
	s_movk_i32 s56, 0x6f
	s_movk_i32 s57, 0x5f
	s_movk_i32 s58, 0x4f
	s_mov_b32 s59, 0x8000
	s_movk_i32 s60, 0xff00
	s_movk_i32 s61, 0xff
	s_mov_b64 s[44:45], 0x80
	s_movk_i32 s62, 0x3fff
	v_lshlrev_b32_e32 v88, 2, v4
	s_mov_b32 s63, 0xf800000
	v_mov_b32_e32 v119, 0x260
	s_mov_b32 s64, 0xc0e00000
	s_movk_i32 s65, 0x80
	s_movk_i32 s66, 0x7fff
	s_movk_i32 s67, 0x7ff
	v_mov_b32_e32 v120, 0x40e00000
	v_mov_b32_e32 v249, -1
	s_branch .LBB0_1085

; __device__ void phase_gather(const Params& p) {
;   const int tid = threadIdx.x, lane = tid & 63, wid = tid >> 6;
;   unsigned char* ws = p.ws;
;   const unsigned char* ub = ws + OFF_XB;
;   const unsigned char* vb = ws + OFF_XB + 16 * MIB;
;   const float* scales = (const float*)(ws + OFF_SCALES);
;   const int* idxg = (const int*)(ws + OFF_IDX);
;   const float* gg = (const float*)(ws + OFF_G);
;   const float* ssq2 = (const float*)(ws + OFF_SSQ2);
;   const bool b5 = (lane & 32) != 0, b4 = (lane & 16) != 0, b3 = (lane & 8) != 0;
;   const int srcl = ((lane & 1) << 3) | (((lane >> 1) & 1) << 4) | (((lane >> 2) & 1) << 5);
;   for (int t = blockIdx.x * 8 + wid; t < T_TOK; t += gridDim.x * 8) {
;     const int id0 = idxg[(size_t)t * 128 + lane], id1 = idxg[(size_t)t * 128 + 64 + lane];
;     const float g0 = gg[(size_t)t * 128 + lane], g1 = gg[(size_t)t * 128 + 64 + lane];
;     const float su0 = scales[id0], su1 = scales[id1], sv0 = scales[16384 + id0], sv1 = scales[16384 + id1];
;     float* orow = p.out + (size_t)t * DM + lane * 32;
;     const float sx = ((const float*)(ws + OFF_WBUF + 8 * MIB))[t];
;     float sq = (lane < 32) ? ssq2[(size_t)t * 32 + lane] : 0.f;
;     sq = wave_sum(sq);
;     const float rs2 = rsqrtf(sq * (1.f / 2048.f) + EPSV);
;     const int* wbuf = (const int*)(ws + OFF_WBUF);
.LBB0_1316:
	s_waitcnt vmcnt(0)
	s_setprio 1
	s_and_saveexec_b64 s[2:3], s[0:1]
	s_cbranch_execz .LBB0_1323
	s_add_u32 s0, s34, 0x1dc90000
	s_addc_u32 s1, s35, 0
	v_writelane_b32 v250, s0, 20
	v_lshlrev_b32_e32 v0, 2, v138
	v_mov_b32_e32 v1, 0
	v_writelane_b32 v250, s1, 21
	s_add_u32 s0, s34, 0xc800000
	s_addc_u32 s1, s35, 0
	v_writelane_b32 v250, s0, 22
	v_cmp_lt_i32_e32 vcc, v89, v84
	v_lshl_add_u64 v[2:3], s[34:35], 0, v[0:1]
	v_writelane_b32 v250, s1, 23
	s_add_u32 s0, s34, 0x17c00000
	s_addc_u32 s1, s35, 0
	v_cndmask_b32_e32 v0, v83, v89, vcc
	v_cmp_lt_i32_e32 vcc, v90, v84
	v_writelane_b32 v250, s0, 24
	v_lshlrev_b32_e32 v126, 2, v0
	v_cndmask_b32_e32 v0, v83, v90, vcc
	v_cmp_lt_i32_e32 vcc, v88, v84
	v_writelane_b32 v250, s1, 25
	v_cmp_gt_u32_e64 s[0:1], 32, v138
	v_lshlrev_b32_e32 v127, 2, v0
	v_cndmask_b32_e32 v0, v83, v88, vcc
	v_cmp_lt_i32_e32 vcc, v87, v84
	v_writelane_b32 v250, s0, 26
	v_lshlrev_b32_e32 v128, 2, v0
	v_cndmask_b32_e32 v0, v83, v87, vcc
	v_cmp_lt_i32_e32 vcc, v86, v84
	v_writelane_b32 v250, s1, 27
	v_lshlrev_b32_e32 v129, 2, v0
	v_cndmask_b32_e32 v0, v83, v86, vcc
	v_cmp_lt_i32_e32 vcc, v85, v84
	s_mov_b64 s[0:1], 0x1da90000
	v_lshlrev_b32_e32 v130, 2, v0
	v_cndmask_b32_e32 v0, v83, v85, vcc
	v_writelane_b32 v250, s68, 28
	v_lshl_add_u64 v[114:115], v[2:3], 0, s[0:1]
	v_lshlrev_b32_e32 v131, 2, v0
	s_mov_b64 s[0:1], 0x1000000
	v_lshlrev_b32_e32 v0, 7, v138
	v_writelane_b32 v250, s69, 29
	v_and_b32_e32 v132, 24, v82
	v_lshl_add_u64 v[116:117], v[72:73], 0, s[0:1]
	v_lshl_add_u64 v[118:119], s[30:31], 0, v[0:1]
	v_lshl_add_u64 v[120:121], s[28:29], 0, v[0:1]
	global_load_dwordx4 v[188:191], v[120:121], off offset:16
	global_load_dwordx4 v[192:195], v[120:121], off offset:32
	global_load_dwordx4 v[196:199], v[120:121], off offset:48
	global_load_dwordx4 v[200:203], v[120:121], off offset:64
	global_load_dwordx4 v[204:207], v[120:121], off offset:80
	global_load_dwordx4 v[208:211], v[120:121], off offset:96
	global_load_dwordx4 v[212:215], v[120:121], off offset:112
	s_mov_b64 s[0:1], 0
	v_mov_b32_e32 v133, 0x358637bd
	s_mov_b32 s55, 0x800000
	s_mov_b32 s33, 0x5010400
	s_mov_b32 s52, 0x7030602
	s_mov_b32 s53, 0x5040100
	s_mov_b32 s54, 0x7060302
	v_writelane_b32 v250, s70, 30
	s_nop 1
	v_writelane_b32 v250, s71, 31
